# final rms-norm hand-written: norm weights loaded once, two rows in flight per wave
# speedup vs baseline: 1.0016x; 1.0016x over previous
.LBB0_1975:
	s_or_b64 exec, exec, s[0:1]
	s_waitcnt lgkmcnt(0)
	s_barrier
	v_readlane_b32 s0, v254, 0
	v_readlane_b32 s1, v254, 1
	v_lshrrev_b32_e32 v2, 6, v0
	v_and_b32_e32 v1, 63, v0
	s_load_dwordx4 s[4:7], s[0:1], 0xe8
	s_load_dwordx2 s[8:9], s[0:1], 0x70
	v_readfirstlane_b32 s10, v2
	s_lshl_b32 s11, s83, 3
	s_add_i32 s11, s11, s10
	s_lshl_b32 s12, s84, 3
	s_add_i32 s13, s11, s12
	s_cmp_gt_i32 s11, 0x3fff
	s_cbranch_scc1 .Lfn_end
	v_lshlrev_b32_e32 v3, 3, v1
	v_lshlrev_b32_e32 v4, 4, v1
	v_xor_b32_e32 v5, 1, v1
	v_lshlrev_b32_e32 v8, 2, v5
	v_xor_b32_e32 v5, 2, v1
	v_lshlrev_b32_e32 v9, 2, v5
	v_xor_b32_e32 v5, 4, v1
	v_lshlrev_b32_e32 v10, 2, v5
	v_xor_b32_e32 v5, 8, v1
	v_lshlrev_b32_e32 v11, 2, v5
	v_xor_b32_e32 v5, 16, v1
	v_lshlrev_b32_e32 v12, 2, v5
	v_xor_b32_e32 v5, 32, v1
	v_lshlrev_b32_e32 v13, 2, v5
	v_mov_b32_e32 v14, 0x358637bd
	s_mov_b32 s22, 0x800000
	s_waitcnt lgkmcnt(0)
	s_add_u32 s6, s6, 0xd580000
	s_addc_u32 s7, s7, 0
	global_load_dwordx4 v[60:63], v4, s[8:9]
	global_load_dwordx4 v[64:67], v4, s[8:9] offset:1024
	global_load_dwordx4 v[68:71], v4, s[8:9] offset:2048
	global_load_dwordx4 v[72:75], v4, s[8:9] offset:3072
	s_min_i32 s14, s11, 0x3fff
	s_lshl_b32 s16, s14, 11
	s_add_u32 s16, s6, s16
	s_addc_u32 s17, s7, 0
	global_load_dwordx2 v[80:81], v3, s[16:17]
	global_load_dwordx2 v[82:83], v3, s[16:17] offset:512
	global_load_dwordx2 v[84:85], v3, s[16:17] offset:1024
	global_load_dwordx2 v[86:87], v3, s[16:17] offset:1536
	s_min_i32 s14, s13, 0x3fff
	s_lshl_b32 s18, s14, 11
	s_add_u32 s18, s6, s18
	s_addc_u32 s19, s7, 0
	global_load_dwordx2 v[88:89], v3, s[18:19]
	global_load_dwordx2 v[90:91], v3, s[18:19] offset:512
	global_load_dwordx2 v[92:93], v3, s[18:19] offset:1024
	global_load_dwordx2 v[94:95], v3, s[18:19] offset:1536
	s_waitcnt vmcnt(4)
.Lfn_loop:
	s_waitcnt vmcnt(8)
	v_lshlrev_b32_e32 v100, 16, v80
	v_and_b32_e32 v101, 0xffff0000, v80
	v_lshlrev_b32_e32 v102, 16, v81
	v_and_b32_e32 v103, 0xffff0000, v81
	v_lshlrev_b32_e32 v104, 16, v82
	v_and_b32_e32 v105, 0xffff0000, v82
	v_lshlrev_b32_e32 v106, 16, v83
	v_and_b32_e32 v107, 0xffff0000, v83
	v_lshlrev_b32_e32 v108, 16, v84
	v_and_b32_e32 v109, 0xffff0000, v84
	v_lshlrev_b32_e32 v110, 16, v85
	v_and_b32_e32 v111, 0xffff0000, v85
	v_lshlrev_b32_e32 v112, 16, v86
	v_and_b32_e32 v113, 0xffff0000, v86
	v_lshlrev_b32_e32 v114, 16, v87
	v_and_b32_e32 v115, 0xffff0000, v87
	v_mul_f32_e32 v116, v101, v101
	v_mul_f32_e32 v117, v105, v105
	v_mul_f32_e32 v118, v109, v109
	v_mul_f32_e32 v119, v113, v113
	v_fmac_f32_e32 v116, v100, v100
	v_fmac_f32_e32 v117, v104, v104
	v_fmac_f32_e32 v118, v108, v108
	v_fmac_f32_e32 v119, v112, v112
	v_fmac_f32_e32 v116, v102, v102
	v_fmac_f32_e32 v117, v106, v106
	v_fmac_f32_e32 v118, v110, v110
	v_fmac_f32_e32 v119, v114, v114
	v_fmac_f32_e32 v116, v103, v103
	v_fmac_f32_e32 v117, v107, v107
	v_fmac_f32_e32 v118, v111, v111
	v_fmac_f32_e32 v119, v115, v115
	v_add_f32_e32 v15, v116, v117
	v_add_f32_e32 v15, v15, v118
	v_add_f32_e32 v15, v15, v119
	ds_bpermute_b32 v36, v8, v15
	s_waitcnt lgkmcnt(0)
	v_add_f32_e32 v15, v15, v36
	ds_bpermute_b32 v36, v9, v15
	s_waitcnt lgkmcnt(0)
	v_add_f32_e32 v15, v15, v36
	ds_bpermute_b32 v36, v10, v15
	s_waitcnt lgkmcnt(0)
	v_add_f32_e32 v15, v15, v36
	ds_bpermute_b32 v36, v11, v15
	s_waitcnt lgkmcnt(0)
	v_add_f32_e32 v15, v15, v36
	ds_bpermute_b32 v36, v12, v15
	s_waitcnt lgkmcnt(0)
	v_add_f32_e32 v15, v15, v36
	ds_bpermute_b32 v36, v13, v15
	s_waitcnt lgkmcnt(0)
	v_add_f32_e32 v15, v15, v36
	v_fmamk_f32 v15, v15, 0x3a800000, v14
	v_mul_f32_e32 v36, 0x4b800000, v15
	v_cmp_gt_f32_e32 vcc, s22, v15
	s_lshl_b32 s20, s11, 12
	s_add_u32 s20, s4, s20
	v_cndmask_b32_e32 v15, v15, v36, vcc
	v_rsq_f32_e32 v15, v15
	s_addc_u32 s21, s5, 0
	s_nop 0
	v_mul_f32_e32 v37, 0x45800000, v15
	v_cndmask_b32_e32 v38, v15, v37, vcc
	v_pk_mul_f32 v[40:41], v[38:39], v[100:101] op_sel_hi:[0,1]
	v_pk_mul_f32 v[42:43], v[38:39], v[102:103] op_sel_hi:[0,1]
	v_pk_mul_f32 v[44:45], v[60:61], v[40:41]
	v_pk_mul_f32 v[46:47], v[62:63], v[42:43]
	global_store_dwordx4 v4, v[44:47], s[20:21]
	v_pk_mul_f32 v[40:41], v[38:39], v[104:105] op_sel_hi:[0,1]
	v_pk_mul_f32 v[42:43], v[38:39], v[106:107] op_sel_hi:[0,1]
	v_pk_mul_f32 v[44:45], v[64:65], v[40:41]
	v_pk_mul_f32 v[46:47], v[66:67], v[42:43]
	global_store_dwordx4 v4, v[44:47], s[20:21] offset:1024
	v_pk_mul_f32 v[40:41], v[38:39], v[108:109] op_sel_hi:[0,1]
	v_pk_mul_f32 v[42:43], v[38:39], v[110:111] op_sel_hi:[0,1]
	v_pk_mul_f32 v[44:45], v[68:69], v[40:41]
	v_pk_mul_f32 v[46:47], v[70:71], v[42:43]
	global_store_dwordx4 v4, v[44:47], s[20:21] offset:2048
	v_pk_mul_f32 v[40:41], v[38:39], v[112:113] op_sel_hi:[0,1]
	v_pk_mul_f32 v[42:43], v[38:39], v[114:115] op_sel_hi:[0,1]
	v_pk_mul_f32 v[44:45], v[72:73], v[40:41]
	v_pk_mul_f32 v[46:47], v[74:75], v[42:43]
	global_store_dwordx4 v4, v[44:47], s[20:21] offset:3072
	s_add_i32 s11, s11, s12
	s_add_i32 s11, s11, s12
	s_min_i32 s14, s11, 0x3fff
	s_lshl_b32 s16, s14, 11
	s_add_u32 s16, s6, s16
	s_addc_u32 s17, s7, 0
	global_load_dwordx2 v[80:81], v3, s[16:17]
	global_load_dwordx2 v[82:83], v3, s[16:17] offset:512
	global_load_dwordx2 v[84:85], v3, s[16:17] offset:1024
	global_load_dwordx2 v[86:87], v3, s[16:17] offset:1536
	s_waitcnt vmcnt(8)
	s_cmp_gt_i32 s13, 0x3fff
	s_cbranch_scc1 .Lfn_end
	v_lshlrev_b32_e32 v100, 16, v88
	v_and_b32_e32 v101, 0xffff0000, v88
	v_lshlrev_b32_e32 v102, 16, v89
	v_and_b32_e32 v103, 0xffff0000, v89
	v_lshlrev_b32_e32 v104, 16, v90
	v_and_b32_e32 v105, 0xffff0000, v90
	v_lshlrev_b32_e32 v106, 16, v91
	v_and_b32_e32 v107, 0xffff0000, v91
	v_lshlrev_b32_e32 v108, 16, v92
	v_and_b32_e32 v109, 0xffff0000, v92
	v_lshlrev_b32_e32 v110, 16, v93
	v_and_b32_e32 v111, 0xffff0000, v93
	v_lshlrev_b32_e32 v112, 16, v94
	v_and_b32_e32 v113, 0xffff0000, v94
	v_lshlrev_b32_e32 v114, 16, v95
	v_and_b32_e32 v115, 0xffff0000, v95
	v_mul_f32_e32 v116, v101, v101
	v_mul_f32_e32 v117, v105, v105
	v_mul_f32_e32 v118, v109, v109
	v_mul_f32_e32 v119, v113, v113
	v_fmac_f32_e32 v116, v100, v100
	v_fmac_f32_e32 v117, v104, v104
	v_fmac_f32_e32 v118, v108, v108
	v_fmac_f32_e32 v119, v112, v112
	v_fmac_f32_e32 v116, v102, v102
	v_fmac_f32_e32 v117, v106, v106
	v_fmac_f32_e32 v118, v110, v110
	v_fmac_f32_e32 v119, v114, v114
	v_fmac_f32_e32 v116, v103, v103
	v_fmac_f32_e32 v117, v107, v107
	v_fmac_f32_e32 v118, v111, v111
	v_fmac_f32_e32 v119, v115, v115
	v_add_f32_e32 v15, v116, v117
	v_add_f32_e32 v15, v15, v118
	v_add_f32_e32 v15, v15, v119
	ds_bpermute_b32 v36, v8, v15
	s_waitcnt lgkmcnt(0)
	v_add_f32_e32 v15, v15, v36
	ds_bpermute_b32 v36, v9, v15
	s_waitcnt lgkmcnt(0)
	v_add_f32_e32 v15, v15, v36
	ds_bpermute_b32 v36, v10, v15
	s_waitcnt lgkmcnt(0)
	v_add_f32_e32 v15, v15, v36
	ds_bpermute_b32 v36, v11, v15
	s_waitcnt lgkmcnt(0)
	v_add_f32_e32 v15, v15, v36
	ds_bpermute_b32 v36, v12, v15
	s_waitcnt lgkmcnt(0)
	v_add_f32_e32 v15, v15, v36
	ds_bpermute_b32 v36, v13, v15
	s_waitcnt lgkmcnt(0)
	v_add_f32_e32 v15, v15, v36
	v_fmamk_f32 v15, v15, 0x3a800000, v14
	v_mul_f32_e32 v36, 0x4b800000, v15
	v_cmp_gt_f32_e32 vcc, s22, v15
	s_lshl_b32 s20, s13, 12
	s_add_u32 s20, s4, s20
	v_cndmask_b32_e32 v15, v15, v36, vcc
	v_rsq_f32_e32 v15, v15
	s_addc_u32 s21, s5, 0
	s_nop 0
	v_mul_f32_e32 v37, 0x45800000, v15
	v_cndmask_b32_e32 v38, v15, v37, vcc
	v_pk_mul_f32 v[40:41], v[38:39], v[100:101] op_sel_hi:[0,1]
	v_pk_mul_f32 v[42:43], v[38:39], v[102:103] op_sel_hi:[0,1]
	v_pk_mul_f32 v[44:45], v[60:61], v[40:41]
	v_pk_mul_f32 v[46:47], v[62:63], v[42:43]
	global_store_dwordx4 v4, v[44:47], s[20:21]
	v_pk_mul_f32 v[40:41], v[38:39], v[104:105] op_sel_hi:[0,1]
	v_pk_mul_f32 v[42:43], v[38:39], v[106:107] op_sel_hi:[0,1]
	v_pk_mul_f32 v[44:45], v[64:65], v[40:41]
	v_pk_mul_f32 v[46:47], v[66:67], v[42:43]
	global_store_dwordx4 v4, v[44:47], s[20:21] offset:1024
	v_pk_mul_f32 v[40:41], v[38:39], v[108:109] op_sel_hi:[0,1]
	v_pk_mul_f32 v[42:43], v[38:39], v[110:111] op_sel_hi:[0,1]
	v_pk_mul_f32 v[44:45], v[68:69], v[40:41]
	v_pk_mul_f32 v[46:47], v[70:71], v[42:43]
	global_store_dwordx4 v4, v[44:47], s[20:21] offset:2048
	v_pk_mul_f32 v[40:41], v[38:39], v[112:113] op_sel_hi:[0,1]
	v_pk_mul_f32 v[42:43], v[38:39], v[114:115] op_sel_hi:[0,1]
	v_pk_mul_f32 v[44:45], v[72:73], v[40:41]
	v_pk_mul_f32 v[46:47], v[74:75], v[42:43]
	global_store_dwordx4 v4, v[44:47], s[20:21] offset:3072
	s_add_i32 s13, s13, s12
	s_add_i32 s13, s13, s12
	s_min_i32 s14, s13, 0x3fff
	s_lshl_b32 s18, s14, 11
	s_add_u32 s18, s6, s18
	s_addc_u32 s19, s7, 0
	global_load_dwordx2 v[88:89], v3, s[18:19]
	global_load_dwordx2 v[90:91], v3, s[18:19] offset:512
	global_load_dwordx2 v[92:93], v3, s[18:19] offset:1024
	global_load_dwordx2 v[94:95], v3, s[18:19] offset:1536
	s_cmp_le_i32 s11, 0x3fff
	s_cbranch_scc1 .Lfn_loop
.Lfn_end:
	s_waitcnt vmcnt(0)
.LBB0_1978:
	s_endpgm
